# speedup vs baseline: 1.0071x; 1.0013x over previous
; __device__ __forceinline__ float bfs(short h) { return __uint_as_float(((unsigned)(u16)h) << 16); }
; __device__ __forceinline__ void phase_g4(PP p, const int g_wid) {
;     ...
;       const u16* sa = p->X + (long)bid * 4 * 65536 + (long)b * 65536 + (unsigned)t2_ * 8;
; #pragma unroll
;       for (int ai = 0; ai < 2; ++ai)
; #pragma unroll
;         for (int m = 0; m < 4; ++m)
; #pragma unroll
;           for (int bj = 0; bj < 2; ++bj) {
;             const int q = (ai * 4 + m) * 2 + bj;
;             bf16x8 s0 = *reinterpret_cast<const bf16x8*>(sa + q * 4096);
;             bf16x8 s1 = *reinterpret_cast<const bf16x8*>(sa + 65536 + q * 4096);
; #pragma unroll
;             for (int n = 0; n < 2; ++n)
; #pragma unroll
;               for (int j = 0; j < 4; ++j)
;                 acc[ai][bj][m][n][j] *= bfs(s0[n * 4 + j]) * __builtin_amdgcn_rcpf(fmaxf(bfs(s1[n * 4 + j]), 1e-30f));
.LBB0_113:
	s_or_b64 exec, exec, s[24:25]
	s_mov_b32 s10, -1
	v_readlane_b32 s37, v254, 63
	v_mbcnt_lo_u32_b32 v0, s10, 0
	v_mbcnt_hi_u32_b32 v0, s10, v0
	v_or_b32_e32 v0, s37, v0
	s_lshl_b64 s[24:25], s[54:55], 17
	s_add_u32 s24, s14, s24
	s_addc_u32 s25, s15, s25
	v_lshlrev_b32_e32 v0, 3, v0
	v_lshl_add_u64 v[2:3], v[0:1], 1, s[24:25]
	v_mov_b64_e32 v[242:243], v[2:3]
	global_load_dwordx4 v[160:163], v[242:243], off
	v_add_co_u32_e32 v240, vcc, 0x20000, v242
	s_nop 1
	v_addc_co_u32_e32 v241, vcc, 0, v243, vcc
	global_load_dwordx4 v[164:167], v[240:241], off
	v_add_co_u32_e32 v240, vcc, 0x2000, v242
	s_nop 1
	v_addc_co_u32_e32 v241, vcc, 0, v243, vcc
	global_load_dwordx4 v[168:171], v[240:241], off
	v_add_co_u32_e32 v240, vcc, 0x22000, v242
	s_nop 1
	v_addc_co_u32_e32 v241, vcc, 0, v243, vcc
	global_load_dwordx4 v[172:175], v[240:241], off
	v_add_co_u32_e32 v240, vcc, 0x4000, v242
	s_nop 1
	v_addc_co_u32_e32 v241, vcc, 0, v243, vcc
	global_load_dwordx4 v[176:179], v[240:241], off
	v_add_co_u32_e32 v240, vcc, 0x24000, v242
	s_nop 1
	v_addc_co_u32_e32 v241, vcc, 0, v243, vcc
	global_load_dwordx4 v[180:183], v[240:241], off
	v_add_co_u32_e32 v240, vcc, 0x6000, v242
	s_nop 1
	v_addc_co_u32_e32 v241, vcc, 0, v243, vcc
	global_load_dwordx4 v[184:187], v[240:241], off
	v_add_co_u32_e32 v240, vcc, 0x26000, v242
	s_nop 1
	v_addc_co_u32_e32 v241, vcc, 0, v243, vcc
	global_load_dwordx4 v[188:191], v[240:241], off
	v_add_co_u32_e32 v240, vcc, 0x8000, v242
	s_nop 1
	v_addc_co_u32_e32 v241, vcc, 0, v243, vcc
	global_load_dwordx4 v[192:195], v[240:241], off
	v_add_co_u32_e32 v240, vcc, 0x28000, v242
	s_nop 1
	v_addc_co_u32_e32 v241, vcc, 0, v243, vcc
	global_load_dwordx4 v[196:199], v[240:241], off
	v_add_co_u32_e32 v240, vcc, 0xa000, v242
	s_nop 1
	v_addc_co_u32_e32 v241, vcc, 0, v243, vcc
	global_load_dwordx4 v[200:203], v[240:241], off
	v_add_co_u32_e32 v240, vcc, 0x2a000, v242
	s_nop 1
	v_addc_co_u32_e32 v241, vcc, 0, v243, vcc
	global_load_dwordx4 v[204:207], v[240:241], off
	v_add_co_u32_e32 v240, vcc, 0xc000, v242
	s_nop 1
	v_addc_co_u32_e32 v241, vcc, 0, v243, vcc
	global_load_dwordx4 v[208:211], v[240:241], off
	v_add_co_u32_e32 v240, vcc, 0x2c000, v242
	s_nop 1
	v_addc_co_u32_e32 v241, vcc, 0, v243, vcc
	global_load_dwordx4 v[212:215], v[240:241], off
	v_add_co_u32_e32 v240, vcc, 0xe000, v242
	s_nop 1
	v_addc_co_u32_e32 v241, vcc, 0, v243, vcc
	global_load_dwordx4 v[216:219], v[240:241], off
	v_add_co_u32_e32 v240, vcc, 0x2e000, v242
	s_nop 1
	v_addc_co_u32_e32 v241, vcc, 0, v243, vcc
	global_load_dwordx4 v[220:223], v[240:241], off
	s_mov_b32 s10, 0x20000
	v_add_co_u32_e32 v136, vcc, s10, v2
	s_nop 0
	v_addc_co_u32_e32 v137, vcc, 0, v3, vcc
	s_movk_i32 s10, 0x2000
	s_mov_b32 s9, 0x22000
	s_mov_b32 s24, 0x28000
	s_add_i32 s54, s54, 1
	s_add_u32 s20, s20, 0x400
	s_addc_u32 s21, s21, 0
	s_add_u32 s22, s22, 0x100000
	s_addc_u32 s23, s23, 0
	s_cmp_eq_u32 s54, 3
	s_waitcnt vmcnt(14)
	v_mov_b64_e32 v[132:133], v[160:161]
	v_mov_b64_e32 v[134:135], v[162:163]
	v_mov_b64_e32 v[136:137], v[164:165]
	v_mov_b64_e32 v[138:139], v[166:167]
	v_and_b32_e32 v145, 0xffff0000, v132
	v_lshlrev_b32_e32 v144, 16, v132
	v_lshlrev_b32_e32 v0, 16, v136
	v_max_f32_e32 v0, v0, v0
	v_max_f32_e32 v0, 0xda24260, v0
	v_rcp_f32_e32 v142, v0
	v_and_b32_e32 v0, 0xffff0000, v136
	v_max_f32_e32 v0, v0, v0
	v_max_f32_e32 v0, 0xda24260, v0
	v_rcp_f32_e32 v143, v0
	v_lshlrev_b32_e32 v0, 16, v137
	v_max_f32_e32 v0, v0, v0
	v_max_f32_e32 v0, 0xda24260, v0
	v_rcp_f32_e32 v136, v0
	v_and_b32_e32 v0, 0xffff0000, v137
	v_max_f32_e32 v0, v0, v0
	v_max_f32_e32 v0, 0xda24260, v0
	v_rcp_f32_e32 v137, v0
	v_pk_mul_f32 v[142:143], v[142:143], v[144:145]
	v_lshlrev_b32_e32 v0, 16, v138
	v_pk_mul_f32 v[8:9], v[8:9], v[142:143]
	v_and_b32_e32 v143, 0xffff0000, v133
	v_lshlrev_b32_e32 v142, 16, v133
	v_max_f32_e32 v0, v0, v0
	v_pk_mul_f32 v[132:133], v[136:137], v[142:143]
	v_max_f32_e32 v0, 0xda24260, v0
	v_pk_mul_f32 v[10:11], v[10:11], v[132:133]
	v_rcp_f32_e32 v132, v0
	v_and_b32_e32 v0, 0xffff0000, v138
	v_max_f32_e32 v0, v0, v0
	v_max_f32_e32 v0, 0xda24260, v0
	v_rcp_f32_e32 v133, v0
	v_lshlrev_b32_e32 v0, 16, v139
	v_and_b32_e32 v137, 0xffff0000, v134
	v_lshlrev_b32_e32 v136, 16, v134
	v_max_f32_e32 v0, v0, v0
	v_pk_mul_f32 v[132:133], v[132:133], v[136:137]
	v_max_f32_e32 v0, 0xda24260, v0
	v_pk_mul_f32 v[4:5], v[4:5], v[132:133]
	v_rcp_f32_e32 v132, v0
	v_and_b32_e32 v0, 0xffff0000, v139
	v_max_f32_e32 v0, v0, v0
	v_max_f32_e32 v0, 0xda24260, v0
	v_rcp_f32_e32 v133, v0
	v_and_b32_e32 v137, 0xffff0000, v135
	v_lshlrev_b32_e32 v136, 16, v135
	v_pk_mul_f32 v[132:133], v[132:133], v[136:137]
	s_nop 0
	v_pk_mul_f32 v[6:7], v[6:7], v[132:133]
	v_add_co_u32_e32 v132, vcc, s10, v2
	s_movk_i32 s10, 0x4000
	s_nop 0
	v_addc_co_u32_e32 v133, vcc, 0, v3, vcc
	v_add_co_u32_e32 v136, vcc, s9, v2
	s_nop 0
	v_addc_co_u32_e32 v137, vcc, 0, v3, vcc
	s_mov_b32 s9, 0x24000
	s_waitcnt vmcnt(12)
; __device__ __forceinline__ float bfs(short h) { return __uint_as_float(((unsigned)(u16)h) << 16); }
; __device__ __forceinline__ void phase_g4(PP p, const int g_wid) {
;     ...
;       const u16* sa = p->X + (long)bid * 4 * 65536 + (long)b * 65536 + (unsigned)t2_ * 8;
; #pragma unroll
;       for (int ai = 0; ai < 2; ++ai)
; #pragma unroll
;         for (int m = 0; m < 4; ++m)
; #pragma unroll
;           for (int bj = 0; bj < 2; ++bj) {
;             const int q = (ai * 4 + m) * 2 + bj;
;             bf16x8 s0 = *reinterpret_cast<const bf16x8*>(sa + q * 4096);
;             bf16x8 s1 = *reinterpret_cast<const bf16x8*>(sa + 65536 + q * 4096);
; #pragma unroll
;             for (int n = 0; n < 2; ++n)
; #pragma unroll
;               for (int j = 0; j < 4; ++j)
;                 acc[ai][bj][m][n][j] *= bfs(s0[n * 4 + j]) * __builtin_amdgcn_rcpf(fmaxf(bfs(s1[n * 4 + j]), 1e-30f));
	v_mov_b64_e32 v[132:133], v[168:169]
	v_mov_b64_e32 v[134:135], v[170:171]
	v_mov_b64_e32 v[136:137], v[172:173]
	v_mov_b64_e32 v[138:139], v[174:175]
	v_and_b32_e32 v145, 0xffff0000, v132
	v_lshlrev_b32_e32 v144, 16, v132
	v_lshlrev_b32_e32 v0, 16, v136
	v_max_f32_e32 v0, v0, v0
	v_max_f32_e32 v0, 0xda24260, v0
	v_rcp_f32_e32 v142, v0
	v_and_b32_e32 v0, 0xffff0000, v136
	v_max_f32_e32 v0, v0, v0
	v_max_f32_e32 v0, 0xda24260, v0
	v_rcp_f32_e32 v143, v0
	v_lshlrev_b32_e32 v0, 16, v137
	v_max_f32_e32 v0, v0, v0
	v_max_f32_e32 v0, 0xda24260, v0
	v_rcp_f32_e32 v136, v0
	v_and_b32_e32 v0, 0xffff0000, v137
	v_max_f32_e32 v0, v0, v0
	v_max_f32_e32 v0, 0xda24260, v0
	v_rcp_f32_e32 v137, v0
	v_pk_mul_f32 v[142:143], v[142:143], v[144:145]
	v_lshlrev_b32_e32 v0, 16, v138
	v_pk_mul_f32 v[16:17], v[16:17], v[142:143]
	v_and_b32_e32 v143, 0xffff0000, v133
	v_lshlrev_b32_e32 v142, 16, v133
	v_max_f32_e32 v0, v0, v0
	v_pk_mul_f32 v[132:133], v[136:137], v[142:143]
	v_max_f32_e32 v0, 0xda24260, v0
	v_pk_mul_f32 v[18:19], v[18:19], v[132:133]
	v_rcp_f32_e32 v132, v0
	v_and_b32_e32 v0, 0xffff0000, v138
	v_max_f32_e32 v0, v0, v0
	v_max_f32_e32 v0, 0xda24260, v0
	v_rcp_f32_e32 v133, v0
	v_lshlrev_b32_e32 v0, 16, v139
	v_and_b32_e32 v137, 0xffff0000, v134
	v_lshlrev_b32_e32 v136, 16, v134
	v_max_f32_e32 v0, v0, v0
	v_pk_mul_f32 v[132:133], v[132:133], v[136:137]
	v_max_f32_e32 v0, 0xda24260, v0
	v_pk_mul_f32 v[12:13], v[12:13], v[132:133]
	v_rcp_f32_e32 v132, v0
	v_and_b32_e32 v0, 0xffff0000, v139
	v_max_f32_e32 v0, v0, v0
	v_max_f32_e32 v0, 0xda24260, v0
	v_rcp_f32_e32 v133, v0
	v_and_b32_e32 v137, 0xffff0000, v135
	v_lshlrev_b32_e32 v136, 16, v135
	v_pk_mul_f32 v[132:133], v[132:133], v[136:137]
	s_nop 0
	v_pk_mul_f32 v[14:15], v[14:15], v[132:133]
	v_add_co_u32_e32 v132, vcc, s10, v2
	s_movk_i32 s10, 0x6000
	s_nop 0
	v_addc_co_u32_e32 v133, vcc, 0, v3, vcc
	v_add_co_u32_e32 v136, vcc, s9, v2
	s_nop 0
	v_addc_co_u32_e32 v137, vcc, 0, v3, vcc
	s_mov_b32 s9, 0x26000
	s_waitcnt vmcnt(10)
	v_mov_b64_e32 v[132:133], v[176:177]
	v_mov_b64_e32 v[134:135], v[178:179]
	v_mov_b64_e32 v[136:137], v[180:181]
	v_mov_b64_e32 v[138:139], v[182:183]
	v_and_b32_e32 v145, 0xffff0000, v132
	v_lshlrev_b32_e32 v144, 16, v132
	v_lshlrev_b32_e32 v0, 16, v136
	v_max_f32_e32 v0, v0, v0
	v_max_f32_e32 v0, 0xda24260, v0
	v_rcp_f32_e32 v142, v0
	v_and_b32_e32 v0, 0xffff0000, v136
	v_max_f32_e32 v0, v0, v0
	v_max_f32_e32 v0, 0xda24260, v0
	v_rcp_f32_e32 v143, v0
	v_lshlrev_b32_e32 v0, 16, v137
	v_max_f32_e32 v0, v0, v0
	v_max_f32_e32 v0, 0xda24260, v0
	v_rcp_f32_e32 v136, v0
	v_and_b32_e32 v0, 0xffff0000, v137
	v_max_f32_e32 v0, v0, v0
	v_max_f32_e32 v0, 0xda24260, v0
	v_rcp_f32_e32 v137, v0
	v_pk_mul_f32 v[142:143], v[142:143], v[144:145]
	v_lshlrev_b32_e32 v0, 16, v138
	v_pk_mul_f32 v[24:25], v[24:25], v[142:143]
	v_and_b32_e32 v143, 0xffff0000, v133
	v_lshlrev_b32_e32 v142, 16, v133
	v_max_f32_e32 v0, v0, v0
	v_pk_mul_f32 v[132:133], v[136:137], v[142:143]
	v_max_f32_e32 v0, 0xda24260, v0
	v_pk_mul_f32 v[26:27], v[26:27], v[132:133]
	v_rcp_f32_e32 v132, v0
	v_and_b32_e32 v0, 0xffff0000, v138
	v_max_f32_e32 v0, v0, v0
	v_max_f32_e32 v0, 0xda24260, v0
	v_rcp_f32_e32 v133, v0
	v_lshlrev_b32_e32 v0, 16, v139
	v_and_b32_e32 v137, 0xffff0000, v134
	v_lshlrev_b32_e32 v136, 16, v134
	v_max_f32_e32 v0, v0, v0
	v_pk_mul_f32 v[132:133], v[132:133], v[136:137]
	v_max_f32_e32 v0, 0xda24260, v0
	v_pk_mul_f32 v[20:21], v[20:21], v[132:133]
	v_rcp_f32_e32 v132, v0
	v_and_b32_e32 v0, 0xffff0000, v139
	v_max_f32_e32 v0, v0, v0
	v_max_f32_e32 v0, 0xda24260, v0
	v_rcp_f32_e32 v133, v0
	v_and_b32_e32 v137, 0xffff0000, v135
	v_lshlrev_b32_e32 v136, 16, v135
	v_pk_mul_f32 v[132:133], v[132:133], v[136:137]
	s_nop 0
	v_pk_mul_f32 v[22:23], v[22:23], v[132:133]
	v_add_co_u32_e32 v132, vcc, s10, v2
	s_mov_b32 s10, 0x8000
	s_nop 0
	v_addc_co_u32_e32 v133, vcc, 0, v3, vcc
	v_add_co_u32_e32 v136, vcc, s9, v2
	s_nop 0
	v_addc_co_u32_e32 v137, vcc, 0, v3, vcc
	s_mov_b32 s9, 0x30000
	s_waitcnt vmcnt(8)
	v_mov_b64_e32 v[132:133], v[184:185]
	v_mov_b64_e32 v[134:135], v[186:187]
	v_mov_b64_e32 v[136:137], v[188:189]
	v_mov_b64_e32 v[138:139], v[190:191]
	v_add_co_u32_e32 v240, vcc, 0x10000, v242
	s_nop 1
	v_addc_co_u32_e32 v241, vcc, 0, v243, vcc
	global_load_dwordx4 v[160:163], v[240:241], off
	v_add_co_u32_e32 v240, vcc, 0x30000, v242
	s_nop 1
	v_addc_co_u32_e32 v241, vcc, 0, v243, vcc
	global_load_dwordx4 v[164:167], v[240:241], off
	v_add_co_u32_e32 v240, vcc, 0x12000, v242
	s_nop 1
	v_addc_co_u32_e32 v241, vcc, 0, v243, vcc
	global_load_dwordx4 v[168:171], v[240:241], off
	v_add_co_u32_e32 v240, vcc, 0x32000, v242
	s_nop 1
	v_addc_co_u32_e32 v241, vcc, 0, v243, vcc
	global_load_dwordx4 v[172:175], v[240:241], off
	v_add_co_u32_e32 v240, vcc, 0x14000, v242
	s_nop 1
	v_addc_co_u32_e32 v241, vcc, 0, v243, vcc
	global_load_dwordx4 v[176:179], v[240:241], off
	v_add_co_u32_e32 v240, vcc, 0x34000, v242
	s_nop 1
	v_addc_co_u32_e32 v241, vcc, 0, v243, vcc
	global_load_dwordx4 v[180:183], v[240:241], off
	v_add_co_u32_e32 v240, vcc, 0x16000, v242
	s_nop 1
	v_addc_co_u32_e32 v241, vcc, 0, v243, vcc
	global_load_dwordx4 v[184:187], v[240:241], off
	v_add_co_u32_e32 v240, vcc, 0x36000, v242
	s_nop 1
	v_addc_co_u32_e32 v241, vcc, 0, v243, vcc
	global_load_dwordx4 v[188:191], v[240:241], off
	v_and_b32_e32 v145, 0xffff0000, v132
	v_lshlrev_b32_e32 v144, 16, v132
	v_lshlrev_b32_e32 v0, 16, v136
	v_max_f32_e32 v0, v0, v0
	v_max_f32_e32 v0, 0xda24260, v0
	v_rcp_f32_e32 v142, v0
	v_and_b32_e32 v0, 0xffff0000, v136
	v_max_f32_e32 v0, v0, v0
	v_max_f32_e32 v0, 0xda24260, v0
	v_rcp_f32_e32 v143, v0
	v_lshlrev_b32_e32 v0, 16, v137
; __device__ __forceinline__ float bfs(short h) { return __uint_as_float(((unsigned)(u16)h) << 16); }
; __device__ __forceinline__ void phase_g4(PP p, const int g_wid) {
;     ...
;       const u16* sa = p->X + (long)bid * 4 * 65536 + (long)b * 65536 + (unsigned)t2_ * 8;
; #pragma unroll
;       for (int ai = 0; ai < 2; ++ai)
; #pragma unroll
;         for (int m = 0; m < 4; ++m)
; #pragma unroll
;           for (int bj = 0; bj < 2; ++bj) {
;             const int q = (ai * 4 + m) * 2 + bj;
;             bf16x8 s0 = *reinterpret_cast<const bf16x8*>(sa + q * 4096);
;             bf16x8 s1 = *reinterpret_cast<const bf16x8*>(sa + 65536 + q * 4096);
; #pragma unroll
;             for (int n = 0; n < 2; ++n)
; #pragma unroll
;               for (int j = 0; j < 4; ++j)
;                 acc[ai][bj][m][n][j] *= bfs(s0[n * 4 + j]) * __builtin_amdgcn_rcpf(fmaxf(bfs(s1[n * 4 + j]), 1e-30f));
	v_max_f32_e32 v0, v0, v0
	v_max_f32_e32 v0, 0xda24260, v0
	v_rcp_f32_e32 v136, v0
	v_and_b32_e32 v0, 0xffff0000, v137
	v_max_f32_e32 v0, v0, v0
	v_max_f32_e32 v0, 0xda24260, v0
	v_rcp_f32_e32 v137, v0
	v_pk_mul_f32 v[142:143], v[142:143], v[144:145]
	v_lshlrev_b32_e32 v0, 16, v138
	v_pk_mul_f32 v[40:41], v[40:41], v[142:143]
	v_and_b32_e32 v143, 0xffff0000, v133
	v_lshlrev_b32_e32 v142, 16, v133
	v_max_f32_e32 v0, v0, v0
	v_pk_mul_f32 v[132:133], v[136:137], v[142:143]
	v_max_f32_e32 v0, 0xda24260, v0
	v_pk_mul_f32 v[42:43], v[42:43], v[132:133]
	v_rcp_f32_e32 v132, v0
	v_and_b32_e32 v0, 0xffff0000, v138
	v_max_f32_e32 v0, v0, v0
	v_max_f32_e32 v0, 0xda24260, v0
	v_rcp_f32_e32 v133, v0
	v_lshlrev_b32_e32 v0, 16, v139
	v_and_b32_e32 v137, 0xffff0000, v134
	v_lshlrev_b32_e32 v136, 16, v134
	v_max_f32_e32 v0, v0, v0
	v_pk_mul_f32 v[132:133], v[132:133], v[136:137]
	v_max_f32_e32 v0, 0xda24260, v0
	v_pk_mul_f32 v[36:37], v[36:37], v[132:133]
	v_rcp_f32_e32 v132, v0
	v_and_b32_e32 v0, 0xffff0000, v139
	v_max_f32_e32 v0, v0, v0
	v_max_f32_e32 v0, 0xda24260, v0
	v_rcp_f32_e32 v133, v0
	v_and_b32_e32 v137, 0xffff0000, v135
	v_lshlrev_b32_e32 v136, 16, v135
	v_pk_mul_f32 v[132:133], v[132:133], v[136:137]
	s_nop 0
	v_pk_mul_f32 v[38:39], v[38:39], v[132:133]
	v_add_co_u32_e32 v132, vcc, s10, v2
	s_mov_b32 s10, 0xa000
	s_nop 0
	v_addc_co_u32_e32 v133, vcc, 0, v3, vcc
	v_add_co_u32_e32 v136, vcc, s24, v2
	s_nop 0
	v_addc_co_u32_e32 v137, vcc, 0, v3, vcc
	s_mov_b32 s24, 0x2a000
	s_waitcnt vmcnt(14)
	v_mov_b64_e32 v[132:133], v[192:193]
	v_mov_b64_e32 v[134:135], v[194:195]
	v_mov_b64_e32 v[136:137], v[196:197]
	v_mov_b64_e32 v[138:139], v[198:199]
	v_and_b32_e32 v145, 0xffff0000, v132
	v_lshlrev_b32_e32 v144, 16, v132
	v_lshlrev_b32_e32 v0, 16, v136
	v_max_f32_e32 v0, v0, v0
	v_max_f32_e32 v0, 0xda24260, v0
	v_rcp_f32_e32 v142, v0
	v_and_b32_e32 v0, 0xffff0000, v136
	v_max_f32_e32 v0, v0, v0
	v_max_f32_e32 v0, 0xda24260, v0
	v_rcp_f32_e32 v143, v0
	v_lshlrev_b32_e32 v0, 16, v137
	v_max_f32_e32 v0, v0, v0
	v_max_f32_e32 v0, 0xda24260, v0
	v_rcp_f32_e32 v136, v0
	v_and_b32_e32 v0, 0xffff0000, v137
	v_max_f32_e32 v0, v0, v0
	v_max_f32_e32 v0, 0xda24260, v0
	v_rcp_f32_e32 v137, v0
	v_pk_mul_f32 v[142:143], v[142:143], v[144:145]
	v_lshlrev_b32_e32 v0, 16, v138
	v_pk_mul_f32 v[56:57], v[56:57], v[142:143]
	v_and_b32_e32 v143, 0xffff0000, v133
	v_lshlrev_b32_e32 v142, 16, v133
	v_max_f32_e32 v0, v0, v0
	v_pk_mul_f32 v[132:133], v[136:137], v[142:143]
	v_max_f32_e32 v0, 0xda24260, v0
	v_pk_mul_f32 v[58:59], v[58:59], v[132:133]
	v_rcp_f32_e32 v132, v0
	v_and_b32_e32 v0, 0xffff0000, v138
	v_max_f32_e32 v0, v0, v0
	v_max_f32_e32 v0, 0xda24260, v0
	v_rcp_f32_e32 v133, v0
	v_lshlrev_b32_e32 v0, 16, v139
	v_and_b32_e32 v137, 0xffff0000, v134
	v_lshlrev_b32_e32 v136, 16, v134
	v_max_f32_e32 v0, v0, v0
	v_pk_mul_f32 v[132:133], v[132:133], v[136:137]
	v_max_f32_e32 v0, 0xda24260, v0
	v_pk_mul_f32 v[52:53], v[52:53], v[132:133]
	v_rcp_f32_e32 v132, v0
	v_and_b32_e32 v0, 0xffff0000, v139
	v_max_f32_e32 v0, v0, v0
	v_max_f32_e32 v0, 0xda24260, v0
	v_rcp_f32_e32 v133, v0
	v_and_b32_e32 v137, 0xffff0000, v135
	v_lshlrev_b32_e32 v136, 16, v135
	v_pk_mul_f32 v[132:133], v[132:133], v[136:137]
	s_nop 0
	v_pk_mul_f32 v[54:55], v[54:55], v[132:133]
	v_add_co_u32_e32 v132, vcc, s10, v2
	s_mov_b32 s10, 0xc000
	s_nop 0
	v_addc_co_u32_e32 v133, vcc, 0, v3, vcc
	v_add_co_u32_e32 v136, vcc, s24, v2
	s_nop 0
	v_addc_co_u32_e32 v137, vcc, 0, v3, vcc
	s_mov_b32 s24, 0x2c000
	s_waitcnt vmcnt(12)
	v_mov_b64_e32 v[132:133], v[200:201]
	v_mov_b64_e32 v[134:135], v[202:203]
	v_mov_b64_e32 v[136:137], v[204:205]
	v_mov_b64_e32 v[138:139], v[206:207]
	v_and_b32_e32 v145, 0xffff0000, v132
	v_lshlrev_b32_e32 v144, 16, v132
	v_lshlrev_b32_e32 v0, 16, v136
	v_max_f32_e32 v0, v0, v0
	v_max_f32_e32 v0, 0xda24260, v0
	v_rcp_f32_e32 v142, v0
	v_and_b32_e32 v0, 0xffff0000, v136
	v_max_f32_e32 v0, v0, v0
	v_max_f32_e32 v0, 0xda24260, v0
	v_rcp_f32_e32 v143, v0
	v_lshlrev_b32_e32 v0, 16, v137
	v_max_f32_e32 v0, v0, v0
	v_max_f32_e32 v0, 0xda24260, v0
	v_rcp_f32_e32 v136, v0
	v_and_b32_e32 v0, 0xffff0000, v137
	v_max_f32_e32 v0, v0, v0
	v_max_f32_e32 v0, 0xda24260, v0
	v_rcp_f32_e32 v137, v0
	v_pk_mul_f32 v[142:143], v[142:143], v[144:145]
	v_lshlrev_b32_e32 v0, 16, v138
	v_pk_mul_f32 v[72:73], v[72:73], v[142:143]
	v_and_b32_e32 v143, 0xffff0000, v133
	v_lshlrev_b32_e32 v142, 16, v133
	v_max_f32_e32 v0, v0, v0
	v_pk_mul_f32 v[132:133], v[136:137], v[142:143]
	v_max_f32_e32 v0, 0xda24260, v0
	v_pk_mul_f32 v[74:75], v[74:75], v[132:133]
	v_rcp_f32_e32 v132, v0
	v_and_b32_e32 v0, 0xffff0000, v138
	v_max_f32_e32 v0, v0, v0
	v_max_f32_e32 v0, 0xda24260, v0
	v_rcp_f32_e32 v133, v0
	v_lshlrev_b32_e32 v0, 16, v139
	v_and_b32_e32 v137, 0xffff0000, v134
	v_lshlrev_b32_e32 v136, 16, v134
	v_max_f32_e32 v0, v0, v0
	v_pk_mul_f32 v[132:133], v[132:133], v[136:137]
	v_max_f32_e32 v0, 0xda24260, v0
	v_pk_mul_f32 v[64:65], v[64:65], v[132:133]
	v_rcp_f32_e32 v132, v0
	v_and_b32_e32 v0, 0xffff0000, v139
	v_max_f32_e32 v0, v0, v0
	v_max_f32_e32 v0, 0xda24260, v0
	v_rcp_f32_e32 v133, v0
	v_and_b32_e32 v137, 0xffff0000, v135
	v_lshlrev_b32_e32 v136, 16, v135
	v_pk_mul_f32 v[132:133], v[132:133], v[136:137]
	s_nop 0
	v_pk_mul_f32 v[66:67], v[66:67], v[132:133]
	v_add_co_u32_e32 v132, vcc, s10, v2
	s_mov_b32 s10, 0xe000
	s_nop 0
	v_addc_co_u32_e32 v133, vcc, 0, v3, vcc
	v_add_co_u32_e32 v136, vcc, s24, v2
	s_nop 0
	v_addc_co_u32_e32 v137, vcc, 0, v3, vcc
	s_mov_b32 s24, 0x2e000
	s_waitcnt vmcnt(10)
; __device__ __forceinline__ float bfs(short h) { return __uint_as_float(((unsigned)(u16)h) << 16); }
; __device__ __forceinline__ void phase_g4(PP p, const int g_wid) {
;     ...
;       const u16* sa = p->X + (long)bid * 4 * 65536 + (long)b * 65536 + (unsigned)t2_ * 8;
; #pragma unroll
;       for (int ai = 0; ai < 2; ++ai)
; #pragma unroll
;         for (int m = 0; m < 4; ++m)
; #pragma unroll
;           for (int bj = 0; bj < 2; ++bj) {
;             const int q = (ai * 4 + m) * 2 + bj;
;             bf16x8 s0 = *reinterpret_cast<const bf16x8*>(sa + q * 4096);
;             bf16x8 s1 = *reinterpret_cast<const bf16x8*>(sa + 65536 + q * 4096);
; #pragma unroll
;             for (int n = 0; n < 2; ++n)
; #pragma unroll
;               for (int j = 0; j < 4; ++j)
;                 acc[ai][bj][m][n][j] *= bfs(s0[n * 4 + j]) * __builtin_amdgcn_rcpf(fmaxf(bfs(s1[n * 4 + j]), 1e-30f));
	v_mov_b64_e32 v[132:133], v[208:209]
	v_mov_b64_e32 v[134:135], v[210:211]
	v_mov_b64_e32 v[136:137], v[212:213]
	v_mov_b64_e32 v[138:139], v[214:215]
	v_and_b32_e32 v145, 0xffff0000, v132
	v_lshlrev_b32_e32 v144, 16, v132
	v_lshlrev_b32_e32 v0, 16, v136
	v_max_f32_e32 v0, v0, v0
	v_max_f32_e32 v0, 0xda24260, v0
	v_rcp_f32_e32 v142, v0
	v_and_b32_e32 v0, 0xffff0000, v136
	v_max_f32_e32 v0, v0, v0
	v_max_f32_e32 v0, 0xda24260, v0
	v_rcp_f32_e32 v143, v0
	v_lshlrev_b32_e32 v0, 16, v137
	v_max_f32_e32 v0, v0, v0
	v_max_f32_e32 v0, 0xda24260, v0
	v_rcp_f32_e32 v136, v0
	v_and_b32_e32 v0, 0xffff0000, v137
	v_max_f32_e32 v0, v0, v0
	v_max_f32_e32 v0, 0xda24260, v0
	v_rcp_f32_e32 v137, v0
	v_pk_mul_f32 v[142:143], v[142:143], v[144:145]
	v_lshlrev_b32_e32 v0, 16, v138
	v_pk_mul_f32 v[88:89], v[88:89], v[142:143]
	v_and_b32_e32 v143, 0xffff0000, v133
	v_lshlrev_b32_e32 v142, 16, v133
	v_max_f32_e32 v0, v0, v0
	v_pk_mul_f32 v[132:133], v[136:137], v[142:143]
	v_max_f32_e32 v0, 0xda24260, v0
	v_pk_mul_f32 v[90:91], v[90:91], v[132:133]
	v_rcp_f32_e32 v132, v0
	v_and_b32_e32 v0, 0xffff0000, v138
	v_max_f32_e32 v0, v0, v0
	v_max_f32_e32 v0, 0xda24260, v0
	v_rcp_f32_e32 v133, v0
	v_lshlrev_b32_e32 v0, 16, v139
	v_and_b32_e32 v137, 0xffff0000, v134
	v_lshlrev_b32_e32 v136, 16, v134
	v_max_f32_e32 v0, v0, v0
	v_pk_mul_f32 v[132:133], v[132:133], v[136:137]
	v_max_f32_e32 v0, 0xda24260, v0
	v_pk_mul_f32 v[84:85], v[84:85], v[132:133]
	v_rcp_f32_e32 v132, v0
	v_and_b32_e32 v0, 0xffff0000, v139
	v_max_f32_e32 v0, v0, v0
	v_max_f32_e32 v0, 0xda24260, v0
	v_rcp_f32_e32 v133, v0
	v_and_b32_e32 v137, 0xffff0000, v135
	v_lshlrev_b32_e32 v136, 16, v135
	v_pk_mul_f32 v[132:133], v[132:133], v[136:137]
	s_nop 0
	v_pk_mul_f32 v[86:87], v[86:87], v[132:133]
	v_add_co_u32_e32 v132, vcc, s10, v2
	s_mov_b32 s10, 0x10000
	s_nop 0
	v_addc_co_u32_e32 v133, vcc, 0, v3, vcc
	v_add_co_u32_e32 v136, vcc, s24, v2
	s_nop 0
	v_addc_co_u32_e32 v137, vcc, 0, v3, vcc
	s_mov_b32 s24, 0x38000
	s_waitcnt vmcnt(8)
	v_mov_b64_e32 v[132:133], v[216:217]
	v_mov_b64_e32 v[134:135], v[218:219]
	v_mov_b64_e32 v[136:137], v[220:221]
	v_mov_b64_e32 v[138:139], v[222:223]
	v_add_co_u32_e32 v240, vcc, 0x18000, v242
	s_nop 1
	v_addc_co_u32_e32 v241, vcc, 0, v243, vcc
	global_load_dwordx4 v[192:195], v[240:241], off
	v_add_co_u32_e32 v240, vcc, 0x38000, v242
	s_nop 1
	v_addc_co_u32_e32 v241, vcc, 0, v243, vcc
	global_load_dwordx4 v[196:199], v[240:241], off
	v_add_co_u32_e32 v240, vcc, 0x1a000, v242
	s_nop 1
	v_addc_co_u32_e32 v241, vcc, 0, v243, vcc
	global_load_dwordx4 v[200:203], v[240:241], off
	v_add_co_u32_e32 v240, vcc, 0x3a000, v242
	s_nop 1
	v_addc_co_u32_e32 v241, vcc, 0, v243, vcc
	global_load_dwordx4 v[204:207], v[240:241], off
	v_add_co_u32_e32 v240, vcc, 0x1c000, v242
	s_nop 1
	v_addc_co_u32_e32 v241, vcc, 0, v243, vcc
	global_load_dwordx4 v[208:211], v[240:241], off
	v_add_co_u32_e32 v240, vcc, 0x3c000, v242
	s_nop 1
	v_addc_co_u32_e32 v241, vcc, 0, v243, vcc
	global_load_dwordx4 v[212:215], v[240:241], off
	v_add_co_u32_e32 v240, vcc, 0x1e000, v242
	s_nop 1
	v_addc_co_u32_e32 v241, vcc, 0, v243, vcc
	global_load_dwordx4 v[216:219], v[240:241], off
	v_add_co_u32_e32 v240, vcc, 0x3e000, v242
	s_nop 1
	v_addc_co_u32_e32 v241, vcc, 0, v243, vcc
	global_load_dwordx4 v[220:223], v[240:241], off
	v_and_b32_e32 v145, 0xffff0000, v132
	v_lshlrev_b32_e32 v144, 16, v132
	v_lshlrev_b32_e32 v0, 16, v136
	v_max_f32_e32 v0, v0, v0
	v_max_f32_e32 v0, 0xda24260, v0
	v_rcp_f32_e32 v142, v0
	v_and_b32_e32 v0, 0xffff0000, v136
	v_max_f32_e32 v0, v0, v0
	v_max_f32_e32 v0, 0xda24260, v0
	v_rcp_f32_e32 v143, v0
	v_lshlrev_b32_e32 v0, 16, v137
	v_max_f32_e32 v0, v0, v0
	v_max_f32_e32 v0, 0xda24260, v0
	v_rcp_f32_e32 v136, v0
	v_and_b32_e32 v0, 0xffff0000, v137
	v_max_f32_e32 v0, v0, v0
	v_max_f32_e32 v0, 0xda24260, v0
	v_rcp_f32_e32 v137, v0
	v_pk_mul_f32 v[142:143], v[142:143], v[144:145]
	v_lshlrev_b32_e32 v0, 16, v138
	v_pk_mul_f32 v[104:105], v[104:105], v[142:143]
	v_and_b32_e32 v143, 0xffff0000, v133
	v_lshlrev_b32_e32 v142, 16, v133
	v_max_f32_e32 v0, v0, v0
	v_pk_mul_f32 v[132:133], v[136:137], v[142:143]
	v_max_f32_e32 v0, 0xda24260, v0
	v_pk_mul_f32 v[106:107], v[106:107], v[132:133]
	v_rcp_f32_e32 v132, v0
	v_and_b32_e32 v0, 0xffff0000, v138
	v_max_f32_e32 v0, v0, v0
	v_max_f32_e32 v0, 0xda24260, v0
	v_rcp_f32_e32 v133, v0
	v_lshlrev_b32_e32 v0, 16, v139
	v_and_b32_e32 v137, 0xffff0000, v134
	v_lshlrev_b32_e32 v136, 16, v134
	v_max_f32_e32 v0, v0, v0
	v_pk_mul_f32 v[132:133], v[132:133], v[136:137]
	v_max_f32_e32 v0, 0xda24260, v0
	v_pk_mul_f32 v[92:93], v[92:93], v[132:133]
	v_rcp_f32_e32 v132, v0
	v_and_b32_e32 v0, 0xffff0000, v139
	v_max_f32_e32 v0, v0, v0
	v_max_f32_e32 v0, 0xda24260, v0
	v_rcp_f32_e32 v133, v0
	v_and_b32_e32 v137, 0xffff0000, v135
	v_lshlrev_b32_e32 v136, 16, v135
	v_pk_mul_f32 v[132:133], v[132:133], v[136:137]
	s_nop 0
	v_pk_mul_f32 v[94:95], v[94:95], v[132:133]
	v_add_co_u32_e32 v132, vcc, s10, v2
	s_mov_b32 s10, 0x14000
	s_nop 0
	v_addc_co_u32_e32 v133, vcc, 0, v3, vcc
	v_add_co_u32_e32 v136, vcc, s9, v2
	s_nop 0
	v_addc_co_u32_e32 v137, vcc, 0, v3, vcc
	s_mov_b32 s9, 0x12000
	s_waitcnt vmcnt(14)
; __device__ __forceinline__ float bfs(short h) { return __uint_as_float(((unsigned)(u16)h) << 16); }
; __device__ __forceinline__ void phase_g4(PP p, const int g_wid) {
;     ...
;       const u16* sa = p->X + (long)bid * 4 * 65536 + (long)b * 65536 + (unsigned)t2_ * 8;
; #pragma unroll
;       for (int ai = 0; ai < 2; ++ai)
; #pragma unroll
;         for (int m = 0; m < 4; ++m)
; #pragma unroll
;           for (int bj = 0; bj < 2; ++bj) {
;             const int q = (ai * 4 + m) * 2 + bj;
;             bf16x8 s0 = *reinterpret_cast<const bf16x8*>(sa + q * 4096);
;             bf16x8 s1 = *reinterpret_cast<const bf16x8*>(sa + 65536 + q * 4096);
; #pragma unroll
;             for (int n = 0; n < 2; ++n)
; #pragma unroll
;               for (int j = 0; j < 4; ++j)
;                 acc[ai][bj][m][n][j] *= bfs(s0[n * 4 + j]) * __builtin_amdgcn_rcpf(fmaxf(bfs(s1[n * 4 + j]), 1e-30f));
	v_mov_b64_e32 v[132:133], v[160:161]
	v_mov_b64_e32 v[134:135], v[162:163]
	v_mov_b64_e32 v[136:137], v[164:165]
	v_mov_b64_e32 v[138:139], v[166:167]
	v_and_b32_e32 v145, 0xffff0000, v132
	v_lshlrev_b32_e32 v144, 16, v132
	v_lshlrev_b32_e32 v0, 16, v136
	v_max_f32_e32 v0, v0, v0
	v_max_f32_e32 v0, 0xda24260, v0
	v_rcp_f32_e32 v142, v0
	v_and_b32_e32 v0, 0xffff0000, v136
	v_max_f32_e32 v0, v0, v0
	v_max_f32_e32 v0, 0xda24260, v0
	v_rcp_f32_e32 v143, v0
	v_lshlrev_b32_e32 v0, 16, v137
	v_max_f32_e32 v0, v0, v0
	v_max_f32_e32 v0, 0xda24260, v0
	v_rcp_f32_e32 v136, v0
	v_and_b32_e32 v0, 0xffff0000, v137
	v_max_f32_e32 v0, v0, v0
	v_max_f32_e32 v0, 0xda24260, v0
	v_rcp_f32_e32 v137, v0
	v_pk_mul_f32 v[142:143], v[142:143], v[144:145]
	v_lshlrev_b32_e32 v0, 16, v138
	v_pk_mul_f32 v[120:121], v[120:121], v[142:143]
	v_and_b32_e32 v143, 0xffff0000, v133
	v_lshlrev_b32_e32 v142, 16, v133
	v_max_f32_e32 v0, v0, v0
	v_pk_mul_f32 v[132:133], v[136:137], v[142:143]
	v_max_f32_e32 v0, 0xda24260, v0
	v_pk_mul_f32 v[122:123], v[122:123], v[132:133]
	v_rcp_f32_e32 v132, v0
	v_and_b32_e32 v0, 0xffff0000, v138
	v_max_f32_e32 v0, v0, v0
	v_max_f32_e32 v0, 0xda24260, v0
	v_rcp_f32_e32 v133, v0
	v_lshlrev_b32_e32 v0, 16, v139
	v_and_b32_e32 v137, 0xffff0000, v134
	v_lshlrev_b32_e32 v136, 16, v134
	v_max_f32_e32 v0, v0, v0
	v_pk_mul_f32 v[132:133], v[132:133], v[136:137]
	v_max_f32_e32 v0, 0xda24260, v0
	v_pk_mul_f32 v[116:117], v[116:117], v[132:133]
	v_rcp_f32_e32 v132, v0
	v_and_b32_e32 v0, 0xffff0000, v139
	v_max_f32_e32 v0, v0, v0
	v_max_f32_e32 v0, 0xda24260, v0
	v_rcp_f32_e32 v133, v0
	v_and_b32_e32 v137, 0xffff0000, v135
	v_lshlrev_b32_e32 v136, 16, v135
	v_pk_mul_f32 v[132:133], v[132:133], v[136:137]
	s_nop 0
	v_pk_mul_f32 v[118:119], v[118:119], v[132:133]
	v_add_co_u32_e32 v132, vcc, s9, v2
	s_mov_b32 s9, 0x32000
	s_nop 0
	v_addc_co_u32_e32 v133, vcc, 0, v3, vcc
	v_add_co_u32_e32 v136, vcc, s9, v2
	s_nop 0
	v_addc_co_u32_e32 v137, vcc, 0, v3, vcc
	s_mov_b32 s9, 0x34000
	s_waitcnt vmcnt(12)
	v_mov_b64_e32 v[132:133], v[168:169]
	v_mov_b64_e32 v[134:135], v[170:171]
	v_mov_b64_e32 v[136:137], v[172:173]
	v_mov_b64_e32 v[138:139], v[174:175]
	v_and_b32_e32 v145, 0xffff0000, v132
	v_lshlrev_b32_e32 v144, 16, v132
	v_lshlrev_b32_e32 v0, 16, v136
	v_max_f32_e32 v0, v0, v0
	v_max_f32_e32 v0, 0xda24260, v0
	v_rcp_f32_e32 v142, v0
	v_and_b32_e32 v0, 0xffff0000, v136
	v_max_f32_e32 v0, v0, v0
	v_max_f32_e32 v0, 0xda24260, v0
	v_rcp_f32_e32 v143, v0
	v_lshlrev_b32_e32 v0, 16, v137
	v_max_f32_e32 v0, v0, v0
	v_max_f32_e32 v0, 0xda24260, v0
	v_rcp_f32_e32 v136, v0
	v_and_b32_e32 v0, 0xffff0000, v137
	v_max_f32_e32 v0, v0, v0
	v_max_f32_e32 v0, 0xda24260, v0
	v_rcp_f32_e32 v137, v0
	v_pk_mul_f32 v[142:143], v[142:143], v[144:145]
	v_lshlrev_b32_e32 v0, 16, v138
	v_pk_mul_f32 v[128:129], v[128:129], v[142:143]
	v_and_b32_e32 v143, 0xffff0000, v133
	v_lshlrev_b32_e32 v142, 16, v133
	v_max_f32_e32 v0, v0, v0
	v_pk_mul_f32 v[132:133], v[136:137], v[142:143]
	v_max_f32_e32 v0, 0xda24260, v0
	v_pk_mul_f32 v[130:131], v[130:131], v[132:133]
	v_rcp_f32_e32 v132, v0
	v_and_b32_e32 v0, 0xffff0000, v138
	v_max_f32_e32 v0, v0, v0
	v_max_f32_e32 v0, 0xda24260, v0
	v_rcp_f32_e32 v133, v0
	v_lshlrev_b32_e32 v0, 16, v139
	v_and_b32_e32 v137, 0xffff0000, v134
	v_lshlrev_b32_e32 v136, 16, v134
	v_max_f32_e32 v0, v0, v0
	v_pk_mul_f32 v[132:133], v[132:133], v[136:137]
	v_max_f32_e32 v0, 0xda24260, v0
	v_pk_mul_f32 v[124:125], v[124:125], v[132:133]
	v_rcp_f32_e32 v132, v0
	v_and_b32_e32 v0, 0xffff0000, v139
	v_max_f32_e32 v0, v0, v0
	v_max_f32_e32 v0, 0xda24260, v0
	v_rcp_f32_e32 v133, v0
	v_and_b32_e32 v137, 0xffff0000, v135
	v_lshlrev_b32_e32 v136, 16, v135
	v_pk_mul_f32 v[132:133], v[132:133], v[136:137]
	s_nop 0
	v_pk_mul_f32 v[126:127], v[126:127], v[132:133]
	v_add_co_u32_e32 v132, vcc, s10, v2
	s_mov_b32 s10, 0x18000
	s_nop 0
	v_addc_co_u32_e32 v133, vcc, 0, v3, vcc
	v_add_co_u32_e32 v136, vcc, s9, v2
	s_nop 0
	v_addc_co_u32_e32 v137, vcc, 0, v3, vcc
	s_mov_b32 s9, 0x16000
	s_waitcnt vmcnt(10)
	v_mov_b64_e32 v[132:133], v[176:177]
	v_mov_b64_e32 v[134:135], v[178:179]
	v_mov_b64_e32 v[136:137], v[180:181]
	v_mov_b64_e32 v[138:139], v[182:183]
	v_and_b32_e32 v145, 0xffff0000, v132
	v_lshlrev_b32_e32 v144, 16, v132
	v_lshlrev_b32_e32 v0, 16, v136
	v_max_f32_e32 v0, v0, v0
	v_max_f32_e32 v0, 0xda24260, v0
	v_rcp_f32_e32 v142, v0
	v_and_b32_e32 v0, 0xffff0000, v136
	v_max_f32_e32 v0, v0, v0
	v_max_f32_e32 v0, 0xda24260, v0
	v_rcp_f32_e32 v143, v0
	v_lshlrev_b32_e32 v0, 16, v137
	v_max_f32_e32 v0, v0, v0
	v_max_f32_e32 v0, 0xda24260, v0
	v_rcp_f32_e32 v136, v0
	v_and_b32_e32 v0, 0xffff0000, v137
	v_max_f32_e32 v0, v0, v0
	v_max_f32_e32 v0, 0xda24260, v0
	v_rcp_f32_e32 v137, v0
	v_pk_mul_f32 v[142:143], v[142:143], v[144:145]
	v_lshlrev_b32_e32 v0, 16, v138
	v_pk_mul_f32 v[112:113], v[112:113], v[142:143]
	v_and_b32_e32 v143, 0xffff0000, v133
	v_lshlrev_b32_e32 v142, 16, v133
	v_max_f32_e32 v0, v0, v0
	v_pk_mul_f32 v[132:133], v[136:137], v[142:143]
	v_max_f32_e32 v0, 0xda24260, v0
	v_pk_mul_f32 v[114:115], v[114:115], v[132:133]
	v_rcp_f32_e32 v132, v0
	v_and_b32_e32 v0, 0xffff0000, v138
	v_max_f32_e32 v0, v0, v0
	v_max_f32_e32 v0, 0xda24260, v0
	v_rcp_f32_e32 v133, v0
	v_lshlrev_b32_e32 v0, 16, v139
	v_and_b32_e32 v137, 0xffff0000, v134
	v_lshlrev_b32_e32 v136, 16, v134
	v_max_f32_e32 v0, v0, v0
	v_pk_mul_f32 v[132:133], v[132:133], v[136:137]
	v_max_f32_e32 v0, 0xda24260, v0
	v_pk_mul_f32 v[108:109], v[108:109], v[132:133]
	v_rcp_f32_e32 v132, v0
	v_and_b32_e32 v0, 0xffff0000, v139
	v_max_f32_e32 v0, v0, v0
	v_max_f32_e32 v0, 0xda24260, v0
	v_rcp_f32_e32 v133, v0
	v_and_b32_e32 v137, 0xffff0000, v135
	v_lshlrev_b32_e32 v136, 16, v135
	v_pk_mul_f32 v[132:133], v[132:133], v[136:137]
	s_nop 0
	v_pk_mul_f32 v[110:111], v[110:111], v[132:133]
	v_add_co_u32_e32 v132, vcc, s9, v2
	s_mov_b32 s9, 0x36000
	s_nop 0
	v_addc_co_u32_e32 v133, vcc, 0, v3, vcc
	v_add_co_u32_e32 v136, vcc, s9, v2
	s_nop 0
	v_addc_co_u32_e32 v137, vcc, 0, v3, vcc
	s_mov_b32 s9, 0x1a000
	s_waitcnt vmcnt(8)
; __device__ __forceinline__ float bfs(short h) { return __uint_as_float(((unsigned)(u16)h) << 16); }
; __device__ __forceinline__ void phase_g4(PP p, const int g_wid) {
;     ...
;       const u16* sa = p->X + (long)bid * 4 * 65536 + (long)b * 65536 + (unsigned)t2_ * 8;
; #pragma unroll
;       for (int ai = 0; ai < 2; ++ai)
; #pragma unroll
;         for (int m = 0; m < 4; ++m)
; #pragma unroll
;           for (int bj = 0; bj < 2; ++bj) {
;             const int q = (ai * 4 + m) * 2 + bj;
;             bf16x8 s0 = *reinterpret_cast<const bf16x8*>(sa + q * 4096);
;             bf16x8 s1 = *reinterpret_cast<const bf16x8*>(sa + 65536 + q * 4096);
; #pragma unroll
;             for (int n = 0; n < 2; ++n)
; #pragma unroll
;               for (int j = 0; j < 4; ++j)
;                 acc[ai][bj][m][n][j] *= bfs(s0[n * 4 + j]) * __builtin_amdgcn_rcpf(fmaxf(bfs(s1[n * 4 + j]), 1e-30f));
	v_mov_b64_e32 v[132:133], v[184:185]
	v_mov_b64_e32 v[134:135], v[186:187]
	v_mov_b64_e32 v[136:137], v[188:189]
	v_mov_b64_e32 v[138:139], v[190:191]
	v_and_b32_e32 v145, 0xffff0000, v132
	v_lshlrev_b32_e32 v144, 16, v132
	v_lshlrev_b32_e32 v0, 16, v136
	v_max_f32_e32 v0, v0, v0
	v_max_f32_e32 v0, 0xda24260, v0
	v_rcp_f32_e32 v142, v0
	v_and_b32_e32 v0, 0xffff0000, v136
	v_max_f32_e32 v0, v0, v0
	v_max_f32_e32 v0, 0xda24260, v0
	v_rcp_f32_e32 v143, v0
	v_lshlrev_b32_e32 v0, 16, v137
	v_max_f32_e32 v0, v0, v0
	v_max_f32_e32 v0, 0xda24260, v0
	v_rcp_f32_e32 v136, v0
	v_and_b32_e32 v0, 0xffff0000, v137
	v_max_f32_e32 v0, v0, v0
	v_max_f32_e32 v0, 0xda24260, v0
	v_rcp_f32_e32 v137, v0
	v_pk_mul_f32 v[142:143], v[142:143], v[144:145]
	v_lshlrev_b32_e32 v0, 16, v138
	v_pk_mul_f32 v[100:101], v[100:101], v[142:143]
	v_and_b32_e32 v143, 0xffff0000, v133
	v_lshlrev_b32_e32 v142, 16, v133
	v_max_f32_e32 v0, v0, v0
	v_pk_mul_f32 v[132:133], v[136:137], v[142:143]
	v_max_f32_e32 v0, 0xda24260, v0
	v_pk_mul_f32 v[102:103], v[102:103], v[132:133]
	v_rcp_f32_e32 v132, v0
	v_and_b32_e32 v0, 0xffff0000, v138
	v_max_f32_e32 v0, v0, v0
	v_max_f32_e32 v0, 0xda24260, v0
	v_rcp_f32_e32 v133, v0
	v_lshlrev_b32_e32 v0, 16, v139
	v_and_b32_e32 v137, 0xffff0000, v134
	v_lshlrev_b32_e32 v136, 16, v134
	v_max_f32_e32 v0, v0, v0
	v_pk_mul_f32 v[132:133], v[132:133], v[136:137]
	v_max_f32_e32 v0, 0xda24260, v0
	v_pk_mul_f32 v[96:97], v[96:97], v[132:133]
	v_rcp_f32_e32 v132, v0
	v_and_b32_e32 v0, 0xffff0000, v139
	v_max_f32_e32 v0, v0, v0
	v_max_f32_e32 v0, 0xda24260, v0
	v_rcp_f32_e32 v133, v0
	v_and_b32_e32 v137, 0xffff0000, v135
	v_lshlrev_b32_e32 v136, 16, v135
	v_pk_mul_f32 v[132:133], v[132:133], v[136:137]
	s_nop 0
	v_pk_mul_f32 v[98:99], v[98:99], v[132:133]
	v_add_co_u32_e32 v132, vcc, s10, v2
	s_mov_b32 s10, 0x1c000
	s_nop 0
	v_addc_co_u32_e32 v133, vcc, 0, v3, vcc
	v_add_co_u32_e32 v136, vcc, s24, v2
	s_nop 0
	v_addc_co_u32_e32 v137, vcc, 0, v3, vcc
	s_mov_b32 s24, 0x3a000
	s_waitcnt vmcnt(6)
	v_mov_b64_e32 v[132:133], v[192:193]
	v_mov_b64_e32 v[134:135], v[194:195]
	v_mov_b64_e32 v[136:137], v[196:197]
	v_mov_b64_e32 v[138:139], v[198:199]
	v_and_b32_e32 v145, 0xffff0000, v132
	v_lshlrev_b32_e32 v144, 16, v132
	v_lshlrev_b32_e32 v0, 16, v136
	v_max_f32_e32 v0, v0, v0
	v_max_f32_e32 v0, 0xda24260, v0
	v_rcp_f32_e32 v142, v0
	v_and_b32_e32 v0, 0xffff0000, v136
	v_max_f32_e32 v0, v0, v0
	v_max_f32_e32 v0, 0xda24260, v0
	v_rcp_f32_e32 v143, v0
	v_lshlrev_b32_e32 v0, 16, v137
	v_max_f32_e32 v0, v0, v0
	v_max_f32_e32 v0, 0xda24260, v0
	v_rcp_f32_e32 v136, v0
	v_and_b32_e32 v0, 0xffff0000, v137
	v_max_f32_e32 v0, v0, v0
	v_max_f32_e32 v0, 0xda24260, v0
	v_rcp_f32_e32 v137, v0
	v_pk_mul_f32 v[142:143], v[142:143], v[144:145]
	v_lshlrev_b32_e32 v0, 16, v138
	v_pk_mul_f32 v[80:81], v[80:81], v[142:143]
	v_and_b32_e32 v143, 0xffff0000, v133
	v_lshlrev_b32_e32 v142, 16, v133
	v_max_f32_e32 v0, v0, v0
	v_pk_mul_f32 v[132:133], v[136:137], v[142:143]
	v_max_f32_e32 v0, 0xda24260, v0
	v_pk_mul_f32 v[82:83], v[82:83], v[132:133]
	v_rcp_f32_e32 v132, v0
	v_and_b32_e32 v0, 0xffff0000, v138
	v_max_f32_e32 v0, v0, v0
	v_max_f32_e32 v0, 0xda24260, v0
	v_rcp_f32_e32 v133, v0
	v_lshlrev_b32_e32 v0, 16, v139
	v_and_b32_e32 v137, 0xffff0000, v134
	v_lshlrev_b32_e32 v136, 16, v134
	v_max_f32_e32 v0, v0, v0
	v_pk_mul_f32 v[132:133], v[132:133], v[136:137]
	v_max_f32_e32 v0, 0xda24260, v0
	v_pk_mul_f32 v[76:77], v[76:77], v[132:133]
	v_rcp_f32_e32 v132, v0
	v_and_b32_e32 v0, 0xffff0000, v139
	v_max_f32_e32 v0, v0, v0
	v_max_f32_e32 v0, 0xda24260, v0
	v_rcp_f32_e32 v133, v0
	v_and_b32_e32 v137, 0xffff0000, v135
	v_lshlrev_b32_e32 v136, 16, v135
	v_pk_mul_f32 v[132:133], v[132:133], v[136:137]
	s_nop 0
	v_pk_mul_f32 v[78:79], v[78:79], v[132:133]
	v_add_co_u32_e32 v132, vcc, s9, v2
	s_nop 1
	v_addc_co_u32_e32 v133, vcc, 0, v3, vcc
	v_add_co_u32_e32 v136, vcc, s24, v2
	s_nop 0
	v_addc_co_u32_e32 v137, vcc, 0, v3, vcc
	s_mov_b32 s24, 0x3c000
	s_waitcnt vmcnt(4)
; __device__ __forceinline__ float bfs(short h) { return __uint_as_float(((unsigned)(u16)h) << 16); }
; __device__ __forceinline__ void phase_g4(PP p, const int g_wid) {
;     ...
;       const u16* sa = p->X + (long)bid * 4 * 65536 + (long)b * 65536 + (unsigned)t2_ * 8;
; #pragma unroll
;       for (int ai = 0; ai < 2; ++ai)
; #pragma unroll
;         for (int m = 0; m < 4; ++m)
; #pragma unroll
;           for (int bj = 0; bj < 2; ++bj) {
;             const int q = (ai * 4 + m) * 2 + bj;
;             bf16x8 s0 = *reinterpret_cast<const bf16x8*>(sa + q * 4096);
;             bf16x8 s1 = *reinterpret_cast<const bf16x8*>(sa + 65536 + q * 4096);
; #pragma unroll
;             for (int n = 0; n < 2; ++n)
; #pragma unroll
;               for (int j = 0; j < 4; ++j)
;                 acc[ai][bj][m][n][j] *= bfs(s0[n * 4 + j]) * __builtin_amdgcn_rcpf(fmaxf(bfs(s1[n * 4 + j]), 1e-30f));
	v_mov_b64_e32 v[132:133], v[200:201]
	v_mov_b64_e32 v[134:135], v[202:203]
	v_mov_b64_e32 v[136:137], v[204:205]
	v_mov_b64_e32 v[138:139], v[206:207]
	v_and_b32_e32 v145, 0xffff0000, v132
	v_lshlrev_b32_e32 v144, 16, v132
	v_lshlrev_b32_e32 v0, 16, v136
	v_max_f32_e32 v0, v0, v0
	v_max_f32_e32 v0, 0xda24260, v0
	v_rcp_f32_e32 v142, v0
	v_and_b32_e32 v0, 0xffff0000, v136
	v_max_f32_e32 v0, v0, v0
	v_max_f32_e32 v0, 0xda24260, v0
	v_rcp_f32_e32 v143, v0
	v_lshlrev_b32_e32 v0, 16, v137
	v_max_f32_e32 v0, v0, v0
	v_max_f32_e32 v0, 0xda24260, v0
	v_rcp_f32_e32 v136, v0
	v_and_b32_e32 v0, 0xffff0000, v137
	v_max_f32_e32 v0, v0, v0
	v_max_f32_e32 v0, 0xda24260, v0
	v_rcp_f32_e32 v137, v0
	v_pk_mul_f32 v[142:143], v[142:143], v[144:145]
	v_lshlrev_b32_e32 v0, 16, v138
	v_pk_mul_f32 v[68:69], v[68:69], v[142:143]
	v_and_b32_e32 v143, 0xffff0000, v133
	v_lshlrev_b32_e32 v142, 16, v133
	v_max_f32_e32 v0, v0, v0
	v_pk_mul_f32 v[132:133], v[136:137], v[142:143]
	v_max_f32_e32 v0, 0xda24260, v0
	v_pk_mul_f32 v[70:71], v[70:71], v[132:133]
	v_rcp_f32_e32 v132, v0
	v_and_b32_e32 v0, 0xffff0000, v138
	v_max_f32_e32 v0, v0, v0
	v_max_f32_e32 v0, 0xda24260, v0
	v_rcp_f32_e32 v133, v0
	v_lshlrev_b32_e32 v0, 16, v139
	v_and_b32_e32 v137, 0xffff0000, v134
	v_lshlrev_b32_e32 v136, 16, v134
	v_max_f32_e32 v0, v0, v0
	v_pk_mul_f32 v[132:133], v[132:133], v[136:137]
	v_max_f32_e32 v0, 0xda24260, v0
	v_pk_mul_f32 v[60:61], v[60:61], v[132:133]
	v_rcp_f32_e32 v132, v0
	v_and_b32_e32 v0, 0xffff0000, v139
	v_max_f32_e32 v0, v0, v0
	v_max_f32_e32 v0, 0xda24260, v0
	v_rcp_f32_e32 v133, v0
	v_and_b32_e32 v137, 0xffff0000, v135
	v_lshlrev_b32_e32 v136, 16, v135
	v_pk_mul_f32 v[132:133], v[132:133], v[136:137]
	s_nop 0
	v_pk_mul_f32 v[62:63], v[62:63], v[132:133]
	v_add_co_u32_e32 v132, vcc, s10, v2
	s_mov_b32 s10, 0x1e000
	s_nop 0
	v_addc_co_u32_e32 v133, vcc, 0, v3, vcc
	v_add_co_u32_e32 v136, vcc, s24, v2
	s_nop 0
	v_addc_co_u32_e32 v137, vcc, 0, v3, vcc
	s_mov_b32 s24, 0x3e000
	s_waitcnt vmcnt(2)
	v_mov_b64_e32 v[132:133], v[208:209]
	v_mov_b64_e32 v[134:135], v[210:211]
	v_mov_b64_e32 v[136:137], v[212:213]
	v_mov_b64_e32 v[138:139], v[214:215]
	v_and_b32_e32 v145, 0xffff0000, v132
	v_lshlrev_b32_e32 v144, 16, v132
	v_lshlrev_b32_e32 v0, 16, v136
	v_max_f32_e32 v0, v0, v0
	v_max_f32_e32 v0, 0xda24260, v0
	v_rcp_f32_e32 v142, v0
	v_and_b32_e32 v0, 0xffff0000, v136
	v_max_f32_e32 v0, v0, v0
	v_max_f32_e32 v0, 0xda24260, v0
	v_rcp_f32_e32 v143, v0
	v_lshlrev_b32_e32 v0, 16, v137
	v_max_f32_e32 v0, v0, v0
	v_max_f32_e32 v0, 0xda24260, v0
	v_rcp_f32_e32 v136, v0
	v_and_b32_e32 v0, 0xffff0000, v137
	v_max_f32_e32 v0, v0, v0
	v_max_f32_e32 v0, 0xda24260, v0
	v_rcp_f32_e32 v137, v0
	v_pk_mul_f32 v[142:143], v[142:143], v[144:145]
	v_lshlrev_b32_e32 v0, 16, v138
	v_pk_mul_f32 v[48:49], v[48:49], v[142:143]
	v_and_b32_e32 v143, 0xffff0000, v133
	v_lshlrev_b32_e32 v142, 16, v133
	v_max_f32_e32 v0, v0, v0
	v_pk_mul_f32 v[132:133], v[136:137], v[142:143]
	v_max_f32_e32 v0, 0xda24260, v0
	v_pk_mul_f32 v[50:51], v[50:51], v[132:133]
	v_rcp_f32_e32 v132, v0
	v_and_b32_e32 v0, 0xffff0000, v138
	v_max_f32_e32 v0, v0, v0
	v_max_f32_e32 v0, 0xda24260, v0
	v_rcp_f32_e32 v133, v0
	v_lshlrev_b32_e32 v0, 16, v139
	v_and_b32_e32 v137, 0xffff0000, v134
	v_lshlrev_b32_e32 v136, 16, v134
	v_max_f32_e32 v0, v0, v0
	v_pk_mul_f32 v[132:133], v[132:133], v[136:137]
	v_max_f32_e32 v0, 0xda24260, v0
	v_pk_mul_f32 v[44:45], v[44:45], v[132:133]
	v_rcp_f32_e32 v132, v0
	v_and_b32_e32 v0, 0xffff0000, v139
	v_max_f32_e32 v0, v0, v0
	v_max_f32_e32 v0, 0xda24260, v0
	v_rcp_f32_e32 v133, v0
	v_and_b32_e32 v137, 0xffff0000, v135
	v_lshlrev_b32_e32 v136, 16, v135
	v_pk_mul_f32 v[132:133], v[132:133], v[136:137]
	s_nop 0
	v_pk_mul_f32 v[46:47], v[46:47], v[132:133]
	v_add_co_u32_e32 v132, vcc, s10, v2
	s_nop 1
	v_addc_co_u32_e32 v133, vcc, 0, v3, vcc
	v_add_co_u32_e32 v2, vcc, s24, v2
	s_nop 0
	v_addc_co_u32_e32 v3, vcc, 0, v3, vcc
	s_waitcnt vmcnt(0)
	v_mov_b64_e32 v[132:133], v[216:217]
	v_mov_b64_e32 v[134:135], v[218:219]
	v_mov_b64_e32 v[136:137], v[220:221]
	v_mov_b64_e32 v[138:139], v[222:223]
	v_and_b32_e32 v143, 0xffff0000, v132
	v_lshlrev_b32_e32 v142, 16, v132
	v_lshlrev_b32_e32 v132, 16, v134
	v_lshlrev_b32_e32 v0, 16, v136
	v_max_f32_e32 v0, v0, v0
	v_max_f32_e32 v0, 0xda24260, v0
	v_rcp_f32_e32 v2, v0
	v_and_b32_e32 v0, 0xffff0000, v136
	v_max_f32_e32 v0, v0, v0
	v_max_f32_e32 v0, 0xda24260, v0
	v_rcp_f32_e32 v3, v0
	v_lshlrev_b32_e32 v0, 16, v137
	v_max_f32_e32 v0, v0, v0
	v_max_f32_e32 v0, 0xda24260, v0
	v_pk_mul_f32 v[2:3], v[2:3], v[142:143]
	v_lshlrev_b32_e32 v136, 16, v133
	v_pk_mul_f32 v[32:33], v[32:33], v[2:3]
	v_rcp_f32_e32 v2, v0
	v_and_b32_e32 v0, 0xffff0000, v137
	v_max_f32_e32 v0, v0, v0
	v_max_f32_e32 v0, 0xda24260, v0
	v_rcp_f32_e32 v3, v0
	v_lshlrev_b32_e32 v0, 16, v138
	v_and_b32_e32 v137, 0xffff0000, v133
	v_max_f32_e32 v0, v0, v0
	v_pk_mul_f32 v[2:3], v[2:3], v[136:137]
	v_max_f32_e32 v0, 0xda24260, v0
	v_pk_mul_f32 v[34:35], v[34:35], v[2:3]
	v_rcp_f32_e32 v2, v0
	v_and_b32_e32 v0, 0xffff0000, v138
	v_max_f32_e32 v0, v0, v0
	v_max_f32_e32 v0, 0xda24260, v0
	v_rcp_f32_e32 v3, v0
	v_lshlrev_b32_e32 v0, 16, v139
	v_and_b32_e32 v133, 0xffff0000, v134
	v_max_f32_e32 v0, v0, v0
	v_pk_mul_f32 v[2:3], v[2:3], v[132:133]
	v_max_f32_e32 v0, 0xda24260, v0
	v_pk_mul_f32 v[28:29], v[28:29], v[2:3]
	v_rcp_f32_e32 v2, v0
	v_and_b32_e32 v0, 0xffff0000, v139
	v_max_f32_e32 v0, v0, v0
	v_max_f32_e32 v0, 0xda24260, v0
	v_rcp_f32_e32 v3, v0
	v_and_b32_e32 v133, 0xffff0000, v135
	v_lshlrev_b32_e32 v132, 16, v135
	v_pk_mul_f32 v[2:3], v[2:3], v[132:133]
	s_nop 0
	v_pk_mul_f32 v[30:31], v[30:31], v[2:3]
	s_cbranch_scc1 .LBB0_99

; __device__ __forceinline__ void phase_ret_o(PP p, const int g_wid, int layer) {
;     ...
;   for (int it = bid; it < NCHUNK * 4; it += gdim) {
;     const int gc = it >> 2, hd = it & 3;
;     int s, c; chunk_decode(gc, s, c);
;     const int L = seq_len(s), base = seq_base(s), t0 = c * 128;
;     const float lgf = log1pf(-expf(p->ret_decay[layer * 8 + hd])), lgb = log1pf(-expf(p->ret_decay[layer * 8 + 4 + hd]));
;     const u16* stf = ST + ((long)(gc * 4 + hd) * 2) * 16384;
;     const u16* stb = stf + 16384;
;     bf16x8 pf[4], pb[4];
; #pragma unroll
;     for (int i = 0; i < 4; ++i) {
;       pf[i] = *reinterpret_cast<const bf16x8*>(stf + (tid + 512 * i) * 8);
;       pb[i] = *reinterpret_cast<const bf16x8*>(stb + (tid + 512 * i) * 8);
;     }
;     __syncthreads();
.LBB0_187:
	s_and_b64 s[6:7], s[6:7], exec
	s_movk_i32 s6, 0x810
	s_cselect_b32 s35, s6, 0x4010
	s_and_b32 s31, s12, 3
	s_or_b32 s6, s31, s30
	s_ashr_i32 s7, s6, 31
	s_lshl_b64 s[6:7], s[6:7], 2
	s_add_u32 s6, s16, s6
	s_addc_u32 s7, s17, s7
	global_load_dword v0, v1, s[6:7]
	global_load_dword v50, v1, s[6:7] offset:16
	s_ashr_i32 s13, s12, 31
	s_lshl_b64 s[6:7], s[12:13], 16
	s_add_u32 s6, s28, s6
	s_addc_u32 s7, s29, s7
	s_add_u32 s8, s6, 0x8000
	s_addc_u32 s9, s7, 0
	v_lshl_add_u64 v[18:19], s[6:7], 0, v[100:101]
	v_lshl_add_u64 v[26:27], s[6:7], 0, v[102:103]
	v_lshl_add_u64 v[34:35], s[6:7], 0, v[104:105]
	v_lshl_add_u64 v[42:43], s[6:7], 0, v[106:107]
	v_lshl_add_u64 v[22:23], s[8:9], 0, v[100:101]
	v_lshl_add_u64 v[30:31], s[8:9], 0, v[102:103]
	v_lshl_add_u64 v[38:39], s[8:9], 0, v[104:105]
	v_lshl_add_u64 v[46:47], s[8:9], 0, v[106:107]
	global_load_dwordx4 v[18:21], v[18:19], off
	s_nop 0
	global_load_dwordx4 v[22:25], v[22:23], off
	s_nop 0
	global_load_dwordx4 v[26:29], v[26:27], off
	s_nop 0
	global_load_dwordx4 v[30:33], v[30:31], off
	s_nop 0
	global_load_dwordx4 v[34:37], v[34:35], off
	s_nop 0
	global_load_dwordx4 v[38:41], v[38:39], off
	s_nop 0
	global_load_dwordx4 v[42:45], v[42:43], off
	s_nop 0
	global_load_dwordx4 v[46:49], v[46:47], off
	s_mov_b32 s6, 0x3fb8aa3b
	s_mov_b32 s8, 0x3f2aaaab
	s_lshl_b32 s13, s20, 7
	s_mov_b32 s39, 0x3fb8aa3b
	s_waitcnt vmcnt(8)
	s_barrier
	v_mul_f32_e32 v51, 0x3fb8aa3b, v0
	v_mul_f32_e32 v52, 0x3fb8aa3b, v50
	v_fma_f32 v53, v0, s6, -v51
	v_rndne_f32_e32 v54, v51
	v_fma_f32 v55, v50, s6, -v52
	v_rndne_f32_e32 v56, v52
	v_fmac_f32_e32 v53, 0x32a5705f, v0
	v_sub_f32_e32 v51, v51, v54
	v_fmac_f32_e32 v55, 0x32a5705f, v50
	v_sub_f32_e32 v52, v52, v56
	v_add_f32_e32 v51, v51, v53
	v_cvt_i32_f32_e32 v54, v54
	v_add_f32_e32 v52, v52, v55
	v_exp_f32_e32 v51, v51
	v_cvt_i32_f32_e32 v56, v56
	v_exp_f32_e32 v52, v52
	s_mov_b32 s6, 0xc2ce8ed0
	v_ldexp_f32 v51, v51, v54
	v_cmp_ngt_f32_e32 vcc, s6, v0
	v_ldexp_f32 v52, v52, v56
	s_nop 0
	v_cndmask_b32_e32 v51, 0, v51, vcc
	v_cmp_ngt_f32_e32 vcc, s6, v50
	s_mov_b32 s6, 0x42b17218
	s_nop 0
	v_cndmask_b32_e32 v52, 0, v52, vcc
	v_cmp_nlt_f32_e32 vcc, s6, v0
	s_nop 1
	v_cndmask_b32_e32 v170, v152, v51, vcc
	v_cmp_nlt_f32_e32 vcc, s6, v50
	v_sub_f32_e32 v77, 1.0, v170
	v_frexp_mant_f32_e32 v0, v77
	v_cndmask_b32_e32 v169, v152, v52, vcc
	v_sub_f32_e32 v76, 1.0, v169
	v_frexp_mant_f32_e32 v50, v76
	v_cmp_gt_f32_e64 s[6:7], s8, v0
	v_cmp_gt_f32_e32 vcc, s8, v50
	s_and_saveexec_b64 s[20:21], s[2:3]
	s_cbranch_execz .LBB0_192
	s_lshl_b32 s8, s31, 8
	s_add_u32 s22, s14, s8
	s_addc_u32 s23, s15, 0
	s_mov_b64 s[24:25], 0
	v_mov_b32_e32 v78, v94
	v_mov_b32_e32 v79, v97
	s_branch .LBB0_190

; __device__ __forceinline__ void phase_ret_o(PP p, const int g_wid, int layer) {
;     ...
;     const int L = seq_len(s), base = seq_base(s), t0 = c * 128;
;     const float lgf = log1pf(-expf(p->ret_decay[layer * 8 + hd])), lgb = log1pf(-expf(p->ret_decay[layer * 8 + 4 + hd]));
;     ...
;     for (int task = tid; task < 2048; task += 512) {
;       int j = task >> 4, e0 = (task & 15) * 8, pos = t0 + j;
;       bf16x8 a;
;       if (pos < L) a = *reinterpret_cast<const bf16x8*>(Pr + (long)(base + pos) * 2048 + 1024 + hd * 128 + e0);
;       else {
; #pragma unroll
;         for (int i = 0; i < 8; ++i) a[i] = 0;
;       }
;       *reinterpret_cast<bf16x8*>(Vs + j * 136 + e0) = a;
;     }
.LBB0_192:
	s_or_b64 exec, exec, s[20:21]
	v_add_f32_e32 v0, -1.0, v77
	v_sub_f32_e32 v50, v0, v77
	v_add_f32_e32 v50, 1.0, v50
	v_sub_f32_e64 v0, -v170, v0
	v_add_f32_e32 v0, v0, v50
	v_cvt_f64_f32_e32 v[50:51], v77
	v_frexp_exp_i32_f64_e32 v50, v[50:51]
	v_subbrev_co_u32_e64 v50, s[6:7], 0, v50, s[6:7]
	v_sub_u32_e32 v51, 0, v50
	v_ldexp_f32 v52, v77, v51
	v_ldexp_f32 v0, v0, v51
	v_add_f32_e32 v51, -1.0, v52
	v_add_f32_e32 v55, 1.0, v52
	v_add_f32_e32 v53, 1.0, v51
	v_add_f32_e32 v56, -1.0, v55
	v_sub_f32_e32 v53, v52, v53
	v_sub_f32_e32 v52, v52, v56
	v_add_f32_e32 v53, v0, v53
	v_add_f32_e32 v0, v0, v52
	v_add_f32_e32 v52, v55, v0
	v_rcp_f32_e32 v56, v52
	v_add_f32_e32 v54, v51, v53
	v_sub_f32_e32 v51, v54, v51
	v_sub_f32_e32 v51, v53, v51
	v_sub_f32_e32 v53, v52, v55
	v_sub_f32_e32 v0, v0, v53
	v_mul_f32_e32 v53, v54, v56
	v_mul_f32_e32 v55, v52, v53
	v_fma_f32 v57, v53, v52, -v55
	v_fmac_f32_e32 v57, v53, v0
	v_add_f32_e32 v58, v55, v57
	v_sub_f32_e32 v59, v54, v58
	v_sub_f32_e32 v54, v54, v59
	v_sub_f32_e32 v55, v58, v55
	v_sub_f32_e32 v54, v54, v58
	v_add_f32_e32 v51, v51, v54
	v_sub_f32_e32 v54, v55, v57
	v_add_f32_e32 v51, v54, v51
	v_add_f32_e32 v54, v59, v51
	v_mul_f32_e32 v55, v56, v54
	v_mul_f32_e32 v57, v52, v55
	v_fma_f32 v52, v55, v52, -v57
	v_fmac_f32_e32 v52, v55, v0
	v_sub_f32_e32 v0, v59, v54
	v_add_f32_e32 v0, v51, v0
	v_add_f32_e32 v51, v57, v52
	v_sub_f32_e32 v58, v54, v51
	v_sub_f32_e32 v54, v54, v58
	v_sub_f32_e32 v57, v51, v57
	v_sub_f32_e32 v51, v54, v51
	v_add_f32_e32 v0, v0, v51
	v_sub_f32_e32 v51, v57, v52
	v_cvt_f32_i32_e32 v50, v50
	v_add_f32_e32 v0, v51, v0
	v_add_f32_e32 v51, v53, v55
	v_add_f32_e32 v0, v58, v0
	v_sub_f32_e32 v52, v51, v53
	v_mul_f32_e32 v0, v56, v0
	v_sub_f32_e32 v52, v55, v52
	v_add_f32_e32 v0, v52, v0
	v_mul_f32_e32 v186, 0x3f317218, v50
	s_mov_b32 s6, 0x3f317218
	v_add_f32_e32 v183, v51, v0
	v_fma_f32 v187, v50, s6, -v186
	v_fmac_f32_e32 v187, 0xb102e308, v50
	v_sub_f32_e32 v50, v183, v51
	v_sub_f32_e32 v0, v0, v50
	v_ldexp_f32 v175, v0, 1
	v_add_f32_e32 v0, -1.0, v76
	v_sub_f32_e32 v50, v0, v76
	v_add_f32_e32 v50, 1.0, v50
	v_sub_f32_e64 v0, -v169, v0
	v_add_f32_e32 v0, v0, v50
	v_cvt_f64_f32_e32 v[50:51], v76
	v_frexp_exp_i32_f64_e32 v50, v[50:51]
	v_mul_f32_e32 v184, v183, v183
	v_subbrev_co_u32_e32 v50, vcc, 0, v50, vcc
	v_fmamk_f32 v52, v184, 0x3e9b6dac, v150
	v_sub_u32_e32 v51, 0, v50
	v_fmaak_f32 v185, v184, v52, 0x3f2aaada
	v_ldexp_f32 v52, v76, v51
	v_ldexp_f32 v0, v0, v51
	v_add_f32_e32 v51, -1.0, v52
	v_add_f32_e32 v55, 1.0, v52
	v_add_f32_e32 v53, 1.0, v51
	v_add_f32_e32 v56, -1.0, v55
	v_sub_f32_e32 v53, v52, v53
	v_sub_f32_e32 v52, v52, v56
	v_add_f32_e32 v53, v0, v53
	v_add_f32_e32 v0, v0, v52
	v_add_f32_e32 v52, v55, v0
	v_rcp_f32_e32 v56, v52
	v_add_f32_e32 v54, v51, v53
	v_sub_f32_e32 v51, v54, v51
	v_sub_f32_e32 v51, v53, v51
	v_sub_f32_e32 v53, v52, v55
	v_sub_f32_e32 v0, v0, v53
	v_mul_f32_e32 v53, v54, v56
	v_mul_f32_e32 v55, v52, v53
	v_fma_f32 v57, v53, v52, -v55
	v_fmac_f32_e32 v57, v53, v0
	v_add_f32_e32 v58, v55, v57
	v_sub_f32_e32 v59, v54, v58
	v_sub_f32_e32 v54, v54, v59
	v_sub_f32_e32 v55, v58, v55
	v_sub_f32_e32 v54, v54, v58
	v_add_f32_e32 v51, v51, v54
	v_sub_f32_e32 v54, v55, v57
	v_add_f32_e32 v51, v54, v51
	v_add_f32_e32 v54, v59, v51
	v_mul_f32_e32 v55, v56, v54
	v_mul_f32_e32 v57, v52, v55
	v_fma_f32 v52, v55, v52, -v57
	v_fmac_f32_e32 v52, v55, v0
	v_sub_f32_e32 v0, v59, v54
	v_add_f32_e32 v0, v51, v0
	v_add_f32_e32 v51, v57, v52
	v_sub_f32_e32 v58, v54, v51
	v_sub_f32_e32 v54, v54, v58
	v_sub_f32_e32 v57, v51, v57
	v_sub_f32_e32 v51, v54, v51
	v_add_f32_e32 v0, v0, v51
	v_sub_f32_e32 v51, v57, v52
	v_cvt_f32_i32_e32 v50, v50
	v_add_f32_e32 v0, v51, v0
	v_add_f32_e32 v51, v53, v55
	v_add_f32_e32 v0, v58, v0
	v_sub_f32_e32 v52, v51, v53
	v_mul_f32_e32 v0, v56, v0
	v_sub_f32_e32 v52, v55, v52
	v_add_f32_e32 v0, v52, v0
	v_mul_f32_e32 v182, 0x3f317218, v50
	v_add_f32_e32 v176, v51, v0
	v_fma_f32 v181, v50, s6, -v182
	v_mul_f32_e32 v179, v176, v176
	v_fmac_f32_e32 v181, 0xb102e308, v50
	v_sub_f32_e32 v50, v176, v51
	v_fmamk_f32 v52, v179, 0x3e9b6dac, v150
	v_sub_f32_e32 v0, v0, v50
	v_xor_b32_e32 v171, 0x80000000, v170
	v_ldexp_f32 v188, v183, 1
	v_and_b32_e32 v173, 0x7fffffff, v170
	v_xor_b32_e32 v172, 0x80000000, v169
	v_fmaak_f32 v178, v179, v52, 0x3f2aaada
	v_ldexp_f32 v180, v176, 1
	v_ldexp_f32 v177, v0, 1
	v_and_b32_e32 v174, 0x7fffffff, v169
	s_and_saveexec_b64 s[6:7], s[4:5]
	s_cbranch_execz .LBB0_197
	s_lshl_b32 s8, s31, 8
	s_add_u32 s8, s14, s8
	s_addc_u32 s9, s15, 0
	v_ashrrev_i32_e32 v202, 4, v97
	v_and_b32_e32 v208, 0x78, v94
	v_lshlrev_b32_e32 v208, 1, v208
	v_mov_b32_e32 v209, 0
	v_add_u32_e32 v203, s13, v202
	v_mul_u32_u24_e32 v204, 0x110, v202
	v_add_u32_e32 v204, v204, v208
	v_add_u32_e32 v206, s34, v203
	v_ashrrev_i32_e32 v207, 31, v206
	v_lshlrev_b64 v[206:207], 12, v[206:207]
	v_lshl_add_u64 v[206:207], s[8:9], 0, v[206:207]
	v_lshl_add_u64 v[206:207], v[206:207], 0, v[208:209]
	s_mov_b64 s[20:21], 0x20000
	v_mov_b32_e32 v210, 0
	v_mov_b32_e32 v211, 0
	v_mov_b32_e32 v212, 0
	v_mov_b32_e32 v213, 0
	v_mov_b32_e32 v214, 0
	v_mov_b32_e32 v215, 0
	v_mov_b32_e32 v216, 0
	v_mov_b32_e32 v217, 0
	v_mov_b32_e32 v218, 0
	v_mov_b32_e32 v219, 0
	v_mov_b32_e32 v220, 0
	v_mov_b32_e32 v221, 0
	v_mov_b32_e32 v222, 0
	v_mov_b32_e32 v223, 0
	v_mov_b32_e32 v224, 0
	v_mov_b32_e32 v225, 0
	v_cmp_gt_i32_e32 vcc, s35, v203
	s_and_saveexec_b64 s[22:23], vcc
	s_cbranch_execz .Lreto_v0
	global_load_dwordx4 v[210:213], v[206:207], off offset:2048
.Lreto_v0:
	s_or_b64 exec, exec, s[22:23]
	v_lshl_add_u64 v[206:207], v[206:207], 0, s[20:21]
	v_add_u32_e32 v205, 32, v203
	v_cmp_gt_i32_e32 vcc, s35, v205
	s_and_saveexec_b64 s[22:23], vcc
	s_cbranch_execz .Lreto_v1
	global_load_dwordx4 v[214:217], v[206:207], off offset:2048
.Lreto_v1:
	s_or_b64 exec, exec, s[22:23]
	v_lshl_add_u64 v[206:207], v[206:207], 0, s[20:21]
	v_add_u32_e32 v205, 64, v203
	v_cmp_gt_i32_e32 vcc, s35, v205
	s_and_saveexec_b64 s[22:23], vcc
	s_cbranch_execz .Lreto_v2
	global_load_dwordx4 v[218:221], v[206:207], off offset:2048
.Lreto_v2:
	s_or_b64 exec, exec, s[22:23]
	v_lshl_add_u64 v[206:207], v[206:207], 0, s[20:21]
	v_add_u32_e32 v205, 96, v203
	v_cmp_gt_i32_e32 vcc, s35, v205
	s_and_saveexec_b64 s[22:23], vcc
	s_cbranch_execz .Lreto_v3
	global_load_dwordx4 v[222:225], v[206:207], off offset:2048
.Lreto_v3:
	s_or_b64 exec, exec, s[22:23]
	s_waitcnt vmcnt(0)
	ds_write_b128 v204, v[210:213] offset:34816
	v_add_u32_e32 v204, 0x2200, v204
	ds_write_b128 v204, v[214:217] offset:34816
	v_add_u32_e32 v204, 0x2200, v204
	ds_write_b128 v204, v[218:221] offset:34816
	v_add_u32_e32 v204, 0x2200, v204
	ds_write_b128 v204, v[222:225] offset:34816
